# v24 + decay table store/load also for the sample chunks (G3 never recomputes b)
# speedup vs baseline: 1.0119x; 1.0028x over previous
; __device__ __forceinline__ Item decode_item(int it) { Item I; if (it < 1024) { const int b = it >> 8; I.h = (it >> 6) & 3; I.row0 = b * SEQ + (it & 63) * 64; I.L = 64; } else { const int j = it - 1024; I.h = j & 3; I.row0 = MP_ROWS + (j >> 2) * 16; I.L = 16; } I.j = it; return I; }
; __device__ __forceinline__ void compute_b(const Params& P, const Item& I, unsigned char* lds) {
;     ...
;     for (int q = 0; q < 3; ++q) if (q < tq) off += qt[q * 128 + dk];
; #pragma unroll
;     for (int i = 0; i < 16; ++i) bsh[(tq * 16 + i) * 128 + dk] = bl[i] + off;
;     __syncthreads();
; }
; __device__ __forceinline__ void gla_g1(const Params& P, unsigned char* lds) {
;     const int tid = threadIdx.x, wid = tid >> 6, lane = tid & 63, fr = lane & 15, fq = lane >> 4;
;     const bf16_t* kg = (const bf16_t*)(P.ws + O_K); const bf16_t* vT = (const bf16_t*)(P.ws + O_VT);
;     bf16_t* KVT = (bf16_t*)(P.ws + O_KVT); float* dec = (float*)(P.ws + O_DEC);
;     const float* bsh = (const float*)(lds + L_BSH); bf16_t* kT = (bf16_t*)(lds + L_KT);
;     for (int it = blockIdx.x; it < NITEM; it += gridDim.x) {
;         const Item I = decode_item(it);
;         compute_b(P, I, lds);
;         { const int dk = tid & 127, tq = tid >> 7; const float blast = bsh[63 * 128 + dk]; float ke[16];
;             bf16_t kraw[16];
; #pragma unroll
;             for (int i = 0; i < 16; ++i) { const int t = tq * 16 + i, tc = t < I.L ? t : I.L - 1; kraw[i] = kg[(size_t)(I.row0 + tc) * KEYD + I.h * DK + dk]; }
.LBB0_1970:
	s_or_b64 exec, exec, s[48:49]
	v_add_f32_e32 v3, v17, v2
	v_add_f32_e32 v4, v18, v2
	ds_write2st64_b32 v113, v3, v4 offset0:16 offset1:18
	v_add_f32_e32 v3, v19, v2
	v_add_f32_e32 v4, v20, v2
	ds_write2st64_b32 v113, v3, v4 offset0:20 offset1:22
	v_add_f32_e32 v3, v21, v2
	v_add_f32_e32 v4, v22, v2
	ds_write2st64_b32 v113, v3, v4 offset0:24 offset1:26
	v_add_f32_e32 v3, v23, v2
	v_add_f32_e32 v4, v24, v2
	ds_write2st64_b32 v113, v3, v4 offset0:28 offset1:30
	v_add_f32_e32 v3, v25, v2
	v_add_f32_e32 v4, v26, v2
	ds_write2st64_b32 v113, v3, v4 offset0:32 offset1:34
	v_add_f32_e32 v3, v27, v2
	v_add_f32_e32 v4, v28, v2
	s_add_i32 s48, s64, -1
	ds_write2st64_b32 v113, v3, v4 offset0:36 offset1:38
	v_add_f32_e32 v3, v29, v2
	v_add_f32_e32 v4, v30, v2
	v_add_f32_e32 v0, v0, v2
	v_add_f32_e32 v1, v1, v2
	v_min_i32_e32 v2, s48, v95
	ds_write2st64_b32 v113, v3, v4 offset0:40 offset1:42
	v_add_u32_e32 v2, s82, v2
	v_min_i32_e32 v4, s48, v96
	s_lshl_b32 s76, s76, 1
	v_ashrrev_i32_e32 v3, 31, v2
	v_add_u32_e32 v4, s82, v4
	ds_write2st64_b32 v113, v0, v1 offset0:44 offset1:46
	v_lshl_add_u64 v[0:1], v[66:67], 0, s[76:77]
	v_lshlrev_b64 v[2:3], 10, v[2:3]
	v_ashrrev_i32_e32 v5, 31, v4
	v_lshl_add_u64 v[2:3], v[0:1], 0, v[2:3]
	v_lshlrev_b64 v[4:5], 10, v[4:5]
	s_waitcnt lgkmcnt(0)
	s_barrier
	v_lshlrev_b32_e32 v190, 6, v210
	v_add_u32_e32 v190, 0x1000, v190
	s_lshl_b32 s98, s65, 9
	v_lshrrev_b32_e32 v191, 3, v210
	v_add_u32_e32 v191, s82, v191
	v_lshlrev_b32_e32 v191, 11, v191
	v_and_b32_e32 v208, 7, v210
	v_lshl_add_u32 v208, v208, 6, s98
	v_add_u32_e32 v191, v191, v208
	s_add_u32 s100, s54, 0x308dc00
	s_addc_u32 s101, s55, 0
	s_mov_b64 s[98:99], exec
	s_cmp_eq_u32 s64, 64
	s_cbranch_scc1 .Lg1_ball
	s_and_b64 exec, exec, s[8:9]
	s_cbranch_execz .Lg1_bskip
.Lg1_ball:
	ds_read_b128 v[192:195], v190
	ds_read_b128 v[196:199], v190 offset:16
	ds_read_b128 v[200:203], v190 offset:32
	ds_read_b128 v[204:207], v190 offset:48
	s_waitcnt lgkmcnt(0)
	global_store_dwordx4 v191, v[192:195], s[100:101]
	global_store_dwordx4 v191, v[196:199], s[100:101] offset:16
	global_store_dwordx4 v191, v[200:203], s[100:101] offset:32
	global_store_dwordx4 v191, v[204:207], s[100:101] offset:48
.Lg1_bskip:
	s_mov_b64 exec, s[98:99]
	v_lshl_add_u64 v[4:5], v[0:1], 0, v[4:5]
	global_load_ushort v18, v[2:3], off
	global_load_ushort v19, v[4:5], off
	v_min_i32_e32 v6, s48, v97
	v_min_i32_e32 v10, s48, v101
	v_add_u32_e32 v6, s82, v6
	v_add_u32_e32 v10, s82, v10
	v_ashrrev_i32_e32 v7, 31, v6
	v_ashrrev_i32_e32 v11, 31, v10
	v_lshlrev_b64 v[6:7], 10, v[6:7]
	v_lshlrev_b64 v[10:11], 10, v[10:11]
	v_min_i32_e32 v12, s48, v102
	v_lshl_add_u64 v[6:7], v[0:1], 0, v[6:7]
	v_min_i32_e32 v8, s48, v98
	v_lshl_add_u64 v[10:11], v[0:1], 0, v[10:11]
	v_add_u32_e32 v12, s82, v12
	v_ashrrev_i32_e32 v13, 31, v12
	global_load_ushort v20, v[6:7], off
	global_load_ushort v24, v[10:11], off
	v_add_u32_e32 v2, s82, v8
	v_min_i32_e32 v4, s48, v99
	v_min_i32_e32 v8, s48, v100
	v_add_u32_e32 v4, s82, v4
	v_add_u32_e32 v8, s82, v8
	v_lshlrev_b64 v[6:7], 10, v[12:13]
	v_min_i32_e32 v12, s48, v103
	v_ashrrev_i32_e32 v3, 31, v2
	v_ashrrev_i32_e32 v5, 31, v4
	v_ashrrev_i32_e32 v9, 31, v8
	v_add_u32_e32 v12, s82, v12
	v_lshlrev_b64 v[2:3], 10, v[2:3]
	v_lshlrev_b64 v[4:5], 10, v[4:5]
	v_lshlrev_b64 v[8:9], 10, v[8:9]
	v_ashrrev_i32_e32 v13, 31, v12
	v_lshl_add_u64 v[2:3], v[0:1], 0, v[2:3]
	v_lshl_add_u64 v[4:5], v[0:1], 0, v[4:5]
	v_lshl_add_u64 v[8:9], v[0:1], 0, v[8:9]
	v_lshlrev_b64 v[12:13], 10, v[12:13]
	global_load_ushort v21, v[2:3], off
	global_load_ushort v22, v[4:5], off
	global_load_ushort v23, v[8:9], off
	v_lshl_add_u64 v[2:3], v[0:1], 0, v[12:13]
	v_min_i32_e32 v12, s48, v104
	v_add_u32_e32 v4, s82, v12
	v_min_i32_e32 v12, s48, v105
	v_add_u32_e32 v12, s82, v12
	v_ashrrev_i32_e32 v13, 31, v12
	v_lshlrev_b64 v[12:13], 10, v[12:13]
	v_lshl_add_u64 v[8:9], v[0:1], 0, v[12:13]
	v_min_i32_e32 v12, s48, v106
	v_add_u32_e32 v10, s82, v12
	v_min_i32_e32 v12, s48, v107
	v_add_u32_e32 v12, s82, v12
	v_ashrrev_i32_e32 v13, 31, v12
	v_lshl_add_u64 v[6:7], v[0:1], 0, v[6:7]
	v_lshlrev_b64 v[12:13], 10, v[12:13]
	global_load_ushort v25, v[6:7], off
	global_load_ushort v26, v[2:3], off
	v_lshl_add_u64 v[6:7], v[0:1], 0, v[12:13]
	v_min_i32_e32 v12, s48, v108
	v_add_u32_e32 v2, s82, v12
	v_ashrrev_i32_e32 v3, 31, v2
	v_lshlrev_b64 v[2:3], 10, v[2:3]
	v_ashrrev_i32_e32 v5, 31, v4
	v_lshl_add_u64 v[12:13], v[0:1], 0, v[2:3]
	v_min_i32_e32 v2, s48, v109
	v_lshlrev_b64 v[4:5], 10, v[4:5]
	v_add_u32_e32 v2, s82, v2
	v_lshl_add_u64 v[4:5], v[0:1], 0, v[4:5]
	v_ashrrev_i32_e32 v3, 31, v2
	v_lshlrev_b64 v[14:15], 10, v[2:3]
	ds_read_b32 v2, v114 offset:4096
	ds_read_b32 v3, v113 offset:4096
	global_load_ushort v27, v[4:5], off
	v_min_i32_e32 v16, s48, v110
	v_ashrrev_i32_e32 v11, 31, v10
	v_add_u32_e32 v16, s82, v16
	v_lshlrev_b64 v[10:11], 10, v[10:11]
	v_ashrrev_i32_e32 v17, 31, v16
	v_lshl_add_u64 v[10:11], v[0:1], 0, v[10:11]
	global_load_ushort v8, v[8:9], off
	v_lshlrev_b64 v[4:5], 10, v[16:17]
	v_lshl_add_u64 v[14:15], v[0:1], 0, v[14:15]
	v_lshl_add_u64 v[0:1], v[0:1], 0, v[4:5]
	global_load_ushort v5, v[10:11], off
	s_nop 0
	global_load_ushort v6, v[6:7], off
	s_waitcnt lgkmcnt(0)
; __device__ __forceinline__ unsigned cvt_pk_bf16(float lo, float hi) { unsigned r; asm volatile("v_cvt_pk_bf16_f32 %0, %1, %2" : "=v"(r) : "v"(lo), "v"(hi)); return r; }
; __device__ __forceinline__ float bf1(bf16_t b) { return __uint_as_float(((unsigned)b) << 16); }
; __device__ __forceinline__ void gla_g1(const Params& P, unsigned char* lds) {
;     ...
;             for (int i = 0; i < 16; ++i) { const int t = tq * 16 + i, tc = t < I.L ? t : I.L - 1; kraw[i] = kg[(size_t)(I.row0 + tc) * KEYD + I.h * DK + dk]; }
; #pragma unroll
;             for (int i = 0; i < 16; ++i) { const int t = tq * 16 + i; const float kv = bf1(kraw[i]) * __expf(blast - bsh[t * 128 + dk]); ke[i] = t < I.L ? kv : 0.f; }
;             u32x4 w0, w1; w0.x = cvt_pk_bf16(ke[0], ke[1]); w0.y = cvt_pk_bf16(ke[2], ke[3]); w0.z = cvt_pk_bf16(ke[4], ke[5]); w0.w = cvt_pk_bf16(ke[6], ke[7]);
;             w1.x = cvt_pk_bf16(ke[8], ke[9]); w1.y = cvt_pk_bf16(ke[10], ke[11]); w1.z = cvt_pk_bf16(ke[12], ke[13]); w1.w = cvt_pk_bf16(ke[14], ke[15]);
;             *(u32x4*)(kT + dk * 72 + tq * 16) = w0; *(u32x4*)(kT + dk * 72 + tq * 16 + 8) = w1;
;             if (tq == 0) dec[(size_t)it * 128 + dk] = __expf(blast); }
	v_sub_f32_e32 v3, v2, v3
	v_mul_f32_e32 v3, 0x3fb8aa3b, v3
	v_exp_f32_e32 v3, v3
	s_waitcnt vmcnt(12)
	v_lshlrev_b32_e32 v4, 16, v18
	v_mul_f32_e32 v3, v3, v4
	s_waitcnt vmcnt(11)
	v_lshlrev_b32_e32 v4, 16, v19
	ds_read_b32 v7, v133 offset:4096
	ds_read_b32 v9, v134 offset:4096
	ds_read_b32 v10, v135 offset:4096
	ds_read_b32 v11, v136 offset:4096
	ds_read_b32 v16, v137 offset:4096
	ds_read_b32 v17, v138 offset:4096
	ds_read_b32 v18, v139 offset:4096
	ds_read_b32 v19, v140 offset:4096
	global_load_ushort v12, v[12:13], off
	s_waitcnt lgkmcnt(7)
	v_sub_f32_e32 v7, v2, v7
	global_load_ushort v0, v[0:1], off
	v_mul_f32_e32 v7, 0x3fb8aa3b, v7
	global_load_ushort v13, v[14:15], off
	s_waitcnt lgkmcnt(6)
	v_sub_f32_e32 v9, v2, v9
	v_exp_f32_e32 v7, v7
	v_mul_f32_e32 v9, 0x3fb8aa3b, v9
	v_exp_f32_e32 v9, v9
	s_waitcnt lgkmcnt(2)
	v_sub_f32_e32 v14, v2, v17
	v_mul_f32_e32 v4, v7, v4
	s_waitcnt vmcnt(13)
	v_lshlrev_b32_e32 v7, 16, v20
	v_mul_f32_e32 v7, v9, v7
	v_sub_f32_e32 v9, v2, v10
	v_mul_f32_e32 v9, 0x3fb8aa3b, v9
	v_sub_f32_e32 v10, v2, v11
	v_exp_f32_e32 v9, v9
	v_mul_f32_e32 v10, 0x3fb8aa3b, v10
	v_exp_f32_e32 v10, v10
	v_sub_f32_e32 v11, v2, v16
	v_mul_f32_e32 v11, 0x3fb8aa3b, v11
	v_exp_f32_e32 v11, v11
	v_mul_f32_e32 v14, 0x3fb8aa3b, v14
	s_waitcnt lgkmcnt(1)
	v_sub_f32_e32 v15, v2, v18
	v_exp_f32_e32 v14, v14
	s_waitcnt vmcnt(11)
	v_lshlrev_b32_e32 v1, 16, v21
	v_mul_f32_e32 v1, v9, v1
	s_waitcnt vmcnt(10)
	v_lshlrev_b32_e32 v9, 16, v22
	v_mul_f32_e32 v9, v10, v9
	s_waitcnt vmcnt(9)
	v_lshlrev_b32_e32 v10, 16, v23
	v_mul_f32_e32 v15, 0x3fb8aa3b, v15
	s_waitcnt lgkmcnt(0)
	v_sub_f32_e32 v16, v2, v19
	ds_read_b32 v17, v141 offset:4096
	ds_read_b32 v18, v142 offset:4096
	ds_read_b32 v19, v143 offset:4096
	ds_read_b32 v20, v144 offset:4096
	ds_read_b32 v21, v145 offset:4096
	ds_read_b32 v22, v146 offset:4096
	ds_read_b32 v23, v147 offset:4096
	v_exp_f32_e32 v15, v15
	v_mul_f32_e32 v16, 0x3fb8aa3b, v16
	s_waitcnt lgkmcnt(6)
	v_sub_f32_e32 v17, v2, v17
	v_exp_f32_e32 v16, v16
	v_mul_f32_e32 v17, 0x3fb8aa3b, v17
	v_mul_f32_e32 v10, v11, v10
	v_lshlrev_b32_e32 v11, 16, v24
	v_exp_f32_e32 v17, v17
	v_mul_f32_e32 v11, v14, v11
	v_cndmask_b32_e64 v4, 0, v4, s[16:17]
	s_waitcnt vmcnt(8)
	v_lshlrev_b32_e32 v14, 16, v25
	v_mul_f32_e32 v14, v15, v14
	s_waitcnt vmcnt(7)
	v_lshlrev_b32_e32 v15, 16, v26
	v_mul_f32_e32 v15, v16, v15
	v_cndmask_b32_e64 v7, 0, v7, s[18:19]
	v_cndmask_b32_e32 v3, 0, v3, vcc
	v_cndmask_b32_e64 v1, 0, v1, s[20:21]
	v_cndmask_b32_e64 v9, 0, v9, s[22:23]
	v_cndmask_b32_e64 v10, 0, v10, s[24:25]
	v_cndmask_b32_e64 v11, 0, v11, s[26:27]
	v_cndmask_b32_e64 v14, 0, v14, s[28:29]
	v_cvt_pk_bf16_f32 v4, v3, v4
	v_cndmask_b32_e64 v15, 0, v15, s[30:31]
	s_waitcnt vmcnt(6)
	v_lshlrev_b32_e32 v16, 16, v27
	v_mul_f32_e32 v16, v17, v16
	s_waitcnt lgkmcnt(5)
	v_sub_f32_e32 v17, v2, v18
	s_waitcnt lgkmcnt(4)
	v_sub_f32_e32 v18, v2, v19
	v_mul_f32_e32 v18, 0x3fb8aa3b, v18
	v_exp_f32_e32 v18, v18
	v_mul_f32_e32 v17, 0x3fb8aa3b, v17
	v_exp_f32_e32 v17, v17
	s_waitcnt vmcnt(5)
	v_lshlrev_b32_e32 v8, 16, v8
	v_cndmask_b32_e64 v16, 0, v16, s[34:35]
	s_waitcnt vmcnt(4)
	v_lshlrev_b32_e32 v5, 16, v5
	v_mul_f32_e32 v5, v18, v5
	v_cndmask_b32_e64 v18, 0, v5, s[38:39]
	s_waitcnt vmcnt(3)
	v_lshlrev_b32_e32 v5, 16, v6
	s_waitcnt lgkmcnt(3)
	v_sub_f32_e32 v6, v2, v20
	v_mul_f32_e32 v8, v17, v8
	v_mul_f32_e32 v6, 0x3fb8aa3b, v6
	v_cndmask_b32_e64 v17, 0, v8, s[36:37]
	v_exp_f32_e32 v6, v6
	s_waitcnt lgkmcnt(2)
	v_sub_f32_e32 v8, v2, v21
	v_mul_f32_e32 v8, 0x3fb8aa3b, v8
	v_exp_f32_e32 v8, v8
	v_mul_f32_e32 v5, v6, v5
	v_cndmask_b32_e64 v19, 0, v5, s[40:41]
	s_waitcnt vmcnt(2)
	v_lshlrev_b32_e32 v5, 16, v12
	s_waitcnt lgkmcnt(1)
	v_sub_f32_e32 v6, v2, v22
	v_mul_f32_e32 v5, v8, v5
	v_mul_f32_e32 v6, 0x3fb8aa3b, v6
	s_waitcnt lgkmcnt(0)
	v_sub_f32_e32 v8, v2, v23
	v_exp_f32_e32 v6, v6
	v_mul_f32_e32 v8, 0x3fb8aa3b, v8
	v_exp_f32_e32 v8, v8
	v_cndmask_b32_e64 v12, 0, v5, s[42:43]
	s_waitcnt vmcnt(0)
	v_lshlrev_b32_e32 v5, 16, v13
	v_mul_f32_e32 v5, v6, v5
	v_lshlrev_b32_e32 v0, 16, v0
	v_cndmask_b32_e64 v13, 0, v5, s[44:45]
	v_mul_f32_e32 v0, v8, v0
	v_cvt_pk_bf16_f32 v5, v7, v1
	v_cvt_pk_bf16_f32 v6, v9, v10
	v_cvt_pk_bf16_f32 v7, v11, v14
	v_cndmask_b32_e64 v0, 0, v0, s[46:47]
	v_cvt_pk_bf16_f32 v8, v15, v16
	v_cvt_pk_bf16_f32 v9, v17, v18
	v_cvt_pk_bf16_f32 v10, v19, v12
	v_cvt_pk_bf16_f32 v11, v13, v0
	ds_write_b128 v115, v[4:7] offset:38912
	ds_write_b128 v115, v[8:11] offset:38928
	s_and_saveexec_b64 s[16:17], s[8:9]
	s_cbranch_execz .LBB0_1972
	v_mul_f32_e32 v0, 0x3fb8aa3b, v2
	v_exp_f32_e32 v2, v0
	s_ashr_i32 s79, s78, 31
	s_lshl_b64 s[18:19], s[78:79], 9
	v_lshl_add_u64 v[0:1], v[68:69], 0, s[18:19]
	global_store_dword v[0:1], v2, off

; __device__ __forceinline__ Item decode_item(int it) { Item I; if (it < 1024) { const int b = it >> 8; I.h = (it >> 6) & 3; I.row0 = b * SEQ + (it & 63) * 64; I.L = 64; } else { const int j = it - 1024; I.h = j & 3; I.row0 = MP_ROWS + (j >> 2) * 16; I.L = 16; } I.j = it; return I; }
; __device__ __forceinline__ void gla_g3(const Params& P, unsigned char* lds) {
;     ...
;     for (int it = blockIdx.x; it < NITEM; it += gridDim.x) {
;         const Item I = decode_item(it);
;         compute_b(P, I, lds);
.LBB0_2142:
	s_cmpk_lt_i32 s48, 0x400
	s_cselect_b64 s[62:63], -1, 0
	s_cmpk_gt_i32 s48, 0x3ff
	s_mov_b64 s[38:39], -1
	s_cbranch_scc0 .LBB0_2173
	s_and_b32 s38, s81, 0x7ffffff0
	s_add_i32 s60, s38, 0x3000
	s_mov_b32 s95, 16
	s_mov_b32 s46, s48
	s_branch .Lg3_loadb

; __device__ __forceinline__ Item decode_item(int it) { Item I; if (it < 1024) { const int b = it >> 8; I.h = (it >> 6) & 3; I.row0 = b * SEQ + (it & 63) * 64; I.L = 64; } else { const int j = it - 1024; I.h = j & 3; I.row0 = MP_ROWS + (j >> 2) * 16; I.L = 16; } I.j = it; return I; }
; __device__ __forceinline__ void gla_g3(const Params& P, unsigned char* lds) {
;     ...
;     for (int it = blockIdx.x; it < NITEM; it += gridDim.x) {
;         const Item I = decode_item(it);
;         compute_b(P, I, lds);
.LBB0_2174:
	s_and_b32 s38, s83, 0xfffff000
	s_and_b32 s39, s86, 0xfc0
	s_lshr_b32 s46, s48, 6
	s_or_b32 s60, s38, s39
	s_mov_b32 s95, 64
	s_branch .Lg3_loadb
.Lg3_loadb:
	s_and_b32 s49, s46, 3
	s_lshl_b32 s46, s49, 8
	s_lshl_b32 s98, s49, 9
	s_add_u32 s100, s54, 0x308dc00
	s_addc_u32 s101, s55, 0
	v_lshrrev_b32_e32 v48, 3, v210
	v_add_u32_e32 v48, s60, v48
	v_lshlrev_b32_e32 v48, 11, v48
	v_and_b32_e32 v49, 7, v210
	v_lshl_add_u32 v49, v49, 6, s98
	v_add_u32_e32 v48, v48, v49
	v_lshlrev_b32_e32 v49, 6, v210
	v_add_u32_e32 v49, 0x1000, v49
	s_mov_b64 s[98:99], exec
	s_cmp_eq_u32 s95, 64
	s_cbranch_scc1 .Lg3_ball
	v_cmp_gt_u32_e32 vcc, 0x80, v210
	s_nop 1
	s_and_b64 exec, exec, vcc
	s_cbranch_execz .Lg3_bskip
.Lg3_ball:
	global_load_dwordx4 v[32:35], v48, s[100:101]
	global_load_dwordx4 v[36:39], v48, s[100:101] offset:16
	global_load_dwordx4 v[40:43], v48, s[100:101] offset:32
	global_load_dwordx4 v[44:47], v48, s[100:101] offset:48
	s_waitcnt vmcnt(0)
	ds_write_b128 v49, v[32:35]
	ds_write_b128 v49, v[36:39] offset:16
	ds_write_b128 v49, v[40:43] offset:32
	ds_write_b128 v49, v[44:47] offset:48
.Lg3_bskip:
	s_mov_b64 exec, s[98:99]
	s_branch .Lg3_tail
